# v16 + late-WG L2 writeback/release moved off the whole-WG path onto decode wave 7 entry (other 7 waves no longer stall behind the serialized L2 writeback)
# speedup vs baseline: 1.0246x; 1.0082x over previous
; #define PSTAMP(i) do { if (PROBE_SEG >= 20 && blockIdx.x == PROBE_BLK && threadIdx.x == 0) ((volatile LAS unsigned long long*)(ctlw + 32))[8 + (i)] = __builtin_amdgcn_s_memrealtime(); } while (0)
; #define QUEUE_LOOP(qi, total, ...) for (;;) { __syncthreads(); if (threadIdx.x == 0) ctlw[16] = __hip_atomic_fetch_add(qbase + 64 * (qi), 1u, __ATOMIC_RELAXED, __HIP_MEMORY_SCOPE_AGENT); \
;         __syncthreads(); const int u = (int)ctlw[16]; if (u >= (total)) break; __VA_ARGS__ }
; template <int MASK> __device__ __forceinline__ void phase3(const Params& p, LAS unsigned char* lds, volatile LAS unsigned* ctlw, int qset) {
;     ...
;     QUEUE_LOOP(0, U_SSDP, { ssd_state_unit<false>(p.ws, p.in[I_ALOG], p.in[I_SCONV], p.in[I_CONVW], p.in[I_CONVB], lds, u >> 5, (u >> 1) & 15, u & 1); })
;     QUEUE_LOOP(4, U_SSDSS, { ssd_state_unit<true>(p.ws, p.in[I_ALOG], p.in[I_SCONV], p.in[I_CONVW], p.in[I_CONVB], lds, u >> 1, 0, u & 1);
;         for (int hh = 0; hh < 4; ++hh)
;             ssd_out_unit<true>(p.ws, p.out, p.in[I_ALOG], p.in[I_DSKIP], p.in[I_SSDNW], p.in[I_SSM], p.in[I_SCONV], p.in[I_CONVW], p.in[I_CONVB], lds, u >> 1, 0, (u & 1) * 4 + hh); })
;     PSTAMP(5);
.LBB0_679:
	v_readlane_b32 s4, v254, 9
	s_sub_i32 s4, s4, 0x80
	s_min_u32 s99, s4, 16
	s_waitcnt vmcnt(0) lgkmcnt(0)
	s_barrier
	s_add_i32 s66, 0, 0x27e40
	v_bfrev_b32_e32 v2, 0.5
	s_mov_b32 s17, 0
	v_mov_b32_e32 v155, 0
	v_mov_b32_e32 v185, s66
	s_movk_i32 s67, 0x2000
	v_bfrev_b32_e32 v157, 1
	s_movk_i32 s74, 0x3600
	s_movk_i32 s75, 0x3000
	s_mov_b64 s[18:19], 0x1000
	s_mov_b64 s[20:21], 0x2000
	s_mov_b64 s[22:23], 0x2400
	s_movk_i32 s76, 0x110
	s_mov_b64 s[26:27], 0x3000
	s_add_i32 s77, 0, 0x1e000
	s_add_i32 s78, 0, 0x1e200
	s_add_i32 s79, 0, 0x1e1fc
	s_add_i32 s84, 0, 0x11000
	s_mov_b32 s85, 0xe000000
	v_lshl_or_b32 v186, v191, 2, v2
	v_mov_b32_e32 v187, 0x3000
	v_mov_b32_e32 v188, 0x8800
	v_mov_b32_e32 v189, 0x9900
	v_mov_b32_e32 v193, 0xaa00
	v_mov_b32_e32 v194, 0xbb00
	v_mov_b32_e32 v195, 0xcc00
	v_mov_b32_e32 v196, 0xdd00
	v_mov_b32_e32 v197, 0xee00
	v_mov_b32_e32 v198, 0xff00
	s_branch .LBB0_682

; #define GROUP_LOOP(qi, total, ...) for (int gi_ = 0;; ++gi_) { if (threadIdx.x == 0) ctlw[22 + (gi_ & 1)] = __hip_atomic_fetch_add(qbase + 64 * (qi), 1u, __ATOMIC_RELAXED, __HIP_MEMORY_SCOPE_AGENT); \
;         group_bar(gb, lane); const int u = (int)ctlw[22 + (gi_ & 1)]; if (u >= (total)) break; __VA_ARGS__ }
; template <int MASK> __device__ __forceinline__ void phase3(const Params& p, LAS unsigned char* lds, volatile LAS unsigned* ctlw, int qset) {
;     ...
;     const unsigned gb0 = __builtin_amdgcn_readfirstlane(ctlw[20]);
;     __syncthreads();
;     {
;         int tid = threadIdx.x; asm volatile("" : "+v"(tid));
;         const int wid = __builtin_amdgcn_readfirstlane(tid >> 6), lane = tid & 63;
;         if (wid < 4) {
;             GroupBar gb; gb.cnt = ctlw + 20; gb.gen = gb0;
;             __builtin_amdgcn_s_setprio(1);
;             GROUP_LOOP(2, U_SB, {
.LBB0_835:
	s_add_i32 s53, 0, 0x27e50
	v_mov_b32_e32 v1, s53
	ds_read_b32 v1, v1
	v_mov_b32_e32 v193, v0
	s_waitcnt vmcnt(0) lgkmcnt(0)
	s_barrier
	s_mov_b32 s45, 0
	v_readfirstlane_b32 s2, v193
	s_ashr_i32 s24, s2, 6
	v_and_b32_e32 v169, 63, v193
	v_readfirstlane_b32 s54, v1
	s_cmp_gt_i32 s24, 3
	v_cmp_eq_u32_e64 s[2:3], 0, v169
	s_cbranch_scc1 .LBB0_961
	s_add_u32 s33, s90, 0xe000000
	s_addc_u32 s52, s91, 0
	s_setprio 1
	v_mov_b32_e32 v3, 0
	v_mov_b32_e32 v194, s53
	s_movk_i32 s55, 0x3600
	s_movk_i32 s62, 0x70
	s_mov_b32 s63, 0xfffff0
	s_movk_i32 s64, 0xc0
	s_movk_i32 s65, 0x60
	s_movk_i32 s66, 0x80
	s_movk_i32 s67, 0xa0
	s_movk_i32 s70, 0xe0
	s_movk_i32 s71, 0x118
	s_mov_b32 s72, 0
	s_branch .LBB0_839

; #define LAS __attribute__((address_space(3)))
; template <int MASK> __device__ __forceinline__ void phase3(const Params& p, LAS unsigned char* lds, volatile LAS unsigned* ctlw, int qset) {
;     ...
;         LAS unsigned char* wlds = lds + (wid < 4 ? wid * 19456 : 77824 + (wid - 4) * 19456);
;         decode_wave_loop((const int*)p.in[I_PT], p.in[I_CK], p.in[I_CV], p.in[I_SBBIAS], p.ws, wlds, qbase + 64 * 1, lane);
.LBB0_961:
	s_cmp_lg_u32 s24, 7
	s_cbranch_scc1 .Llz_skip
	v_readlane_b32 s12, v254, 9
	s_cmpk_gt_i32 s12, 0x93
	s_cbranch_scc1 .Llz_skip
	s_and_saveexec_b64 s[10:11], s[2:3]
	buffer_wbl2 sc1
	v_mov_b32_e32 v2, 0xa00
	v_mov_b32_e32 v3, 1
	s_waitcnt vmcnt(0)
	global_atomic_add v2, v3, s[90:91]
	global_atomic_add v2, v3, s[90:91] offset:-512
	s_waitcnt vmcnt(0)
	s_or_b64 exec, exec, s[10:11]
